# adds prompt conv LN loop: both column halves' operand loads issued together (second drain removed)
# speedup vs baseline: 1.0009x; 1.0009x over previous
.LBB0_635:
	ds_read_b128 v[14:17], v40
	ds_read_b128 v[10:13], v40 offset:16
	ds_read_b128 v[6:9], v40 offset:2048
	s_waitcnt lgkmcnt(2)
	v_mov_b32_e32 v2, v15
	v_mov_b32_e32 v3, v16
	v_mov_b32_e32 v4, v14
	v_mov_b32_e32 v5, v17
	v_pk_add_f32 v[2:3], v[2:3], v[4:5]
	s_waitcnt lgkmcnt(1)
	v_mov_b32_e32 v4, v10
	v_add_f32_e32 v2, v2, v3
	v_add_f32_e32 v28, 0, v2
	v_mov_b32_e32 v2, v11
	v_mov_b32_e32 v3, v12
	v_mov_b32_e32 v5, v13
	v_pk_add_f32 v[2:3], v[2:3], v[4:5]
	s_nop 0
	v_pk_add_f32 v[30:31], v[2:3], v[2:3] op_sel:[0,1] op_sel_hi:[1,0]
	ds_read_b128 v[2:5], v40 offset:2064
	s_waitcnt lgkmcnt(1)
	v_add_f32_e32 v32, v6, v7
	v_add_f32_e32 v42, v8, v9
	v_add_u32_e32 v40, 0x8000, v40
	s_waitcnt lgkmcnt(0)
	v_mov_b32_e32 v29, v2
	v_mov_b32_e32 v31, v3
	v_mov_b32_e32 v33, v4
	v_mov_b32_e32 v43, v5
	v_pk_add_f32 v[28:29], v[28:29], v[30:31]
	v_pk_add_f32 v[30:31], v[32:33], v[42:43]
	s_nop 0
	v_pk_add_f32 v[28:29], v[28:29], v[30:31]
	s_nop 0
	v_add_f32_e32 v26, v28, v29
	ds_bpermute_b32 v28, v27, v26
	s_waitcnt lgkmcnt(0)
	v_add_f32_e32 v26, v26, v28
	ds_bpermute_b32 v28, v34, v26
	s_waitcnt lgkmcnt(0)
	v_add_f32_e32 v26, v26, v28
	ds_bpermute_b32 v28, v35, v26
	s_waitcnt lgkmcnt(0)
	v_add_f32_e32 v26, v26, v28
	ds_bpermute_b32 v28, v36, v26
	s_waitcnt lgkmcnt(0)
	v_add_f32_e32 v26, v26, v28
	ds_bpermute_b32 v28, v37, v26
	s_waitcnt lgkmcnt(0)
	v_add_f32_e32 v26, v26, v28
	ds_bpermute_b32 v28, v38, v26
	s_waitcnt lgkmcnt(0)
	v_add_f32_e32 v26, v26, v28
	v_fmamk_f32 v33, v26, 0xba800000, v15
	v_fmamk_f32 v32, v26, 0xba800000, v14
	v_fmamk_f32 v17, v26, 0xba800000, v17
	v_fmac_f32_e32 v16, 0xba800000, v26
	v_pk_mul_f32 v[14:15], v[16:17], v[16:17]
	v_pk_mul_f32 v[28:29], v[32:33], v[32:33]
	v_fmamk_f32 v13, v26, 0xba800000, v13
	v_pk_mov_b32 v[30:31], v[28:29], v[14:15] op_sel:[1,0]
	v_mov_b32_e32 v29, v15
	v_pk_add_f32 v[14:15], v[30:31], v[28:29]
	v_fmamk_f32 v31, v26, 0xba800000, v11
	v_fmamk_f32 v30, v26, 0xba800000, v10
	v_fmac_f32_e32 v12, 0xba800000, v26
	v_pk_add_f32 v[28:29], v[14:15], v[14:15] op_sel_hi:[0,1]
	v_pk_mul_f32 v[10:11], v[12:13], v[12:13]
	v_pk_mul_f32 v[14:15], v[30:31], v[30:31]
	v_fmac_f32_e32 v8, 0xba800000, v26
	v_pk_mov_b32 v[42:43], v[14:15], v[10:11] op_sel:[1,0]
	v_mov_b32_e32 v15, v11
	v_pk_add_f32 v[10:11], v[42:43], v[14:15]
	v_fmamk_f32 v14, v26, 0xba800000, v6
	v_fmamk_f32 v15, v26, 0xba800000, v7
	v_mul_f32_e32 v6, v14, v14
	v_pk_fma_f32 v[6:7], v[14:15], v[14:15], v[6:7] op_sel_hi:[1,1,0]
	v_fmamk_f32 v9, v26, 0xba800000, v9
	v_mul_f32_e32 v6, v8, v8
	v_pk_add_f32 v[42:43], v[10:11], v[10:11] op_sel_hi:[0,1]
	v_pk_fma_f32 v[44:45], v[8:9], v[8:9], v[6:7] op_sel_hi:[1,1,0]
	v_fmamk_f32 v11, v26, 0xba800000, v5
	v_fmamk_f32 v10, v26, 0xba800000, v4
	v_fmamk_f32 v3, v26, 0xba800000, v3
	v_fmac_f32_e32 v2, 0xba800000, v26
	v_mul_f32_e32 v6, v2, v2
	v_mul_f32_e32 v44, v3, v3
	v_mul_f32_e32 v28, v10, v10
	v_mul_f32_e32 v42, v11, v11
	v_pk_add_f32 v[4:5], v[6:7], v[44:45]
	v_pk_add_f32 v[6:7], v[28:29], v[42:43]
	s_nop 0
	v_pk_add_f32 v[4:5], v[4:5], v[6:7]
	s_nop 0
	v_add_f32_e32 v4, v4, v5
	ds_bpermute_b32 v5, v27, v4
	s_waitcnt lgkmcnt(0)
	v_add_f32_e32 v4, v4, v5
	ds_bpermute_b32 v5, v34, v4
	s_waitcnt lgkmcnt(0)
	v_add_f32_e32 v4, v4, v5
	ds_bpermute_b32 v5, v35, v4
	s_waitcnt lgkmcnt(0)
	v_add_f32_e32 v4, v4, v5
	ds_bpermute_b32 v5, v36, v4
	s_waitcnt lgkmcnt(0)
	v_add_f32_e32 v4, v4, v5
	ds_bpermute_b32 v5, v37, v4
	s_waitcnt lgkmcnt(0)
	v_add_f32_e32 v4, v4, v5
	ds_bpermute_b32 v5, v38, v4
	s_waitcnt lgkmcnt(0)
	v_add_f32_e32 v4, v4, v5
	v_fmamk_f32 v4, v4, 0x3a800000, v171
	v_cmp_gt_f32_e32 vcc, s9, v4
	v_mul_f32_e32 v5, 0x4f800000, v4
	s_nop 0
	v_cndmask_b32_e32 v4, v4, v5, vcc
	v_sqrt_f32_e32 v5, v4
	s_nop 0
	v_add_u32_e32 v6, -1, v5
	v_fma_f32 v7, -v6, v5, v4
	v_cmp_ge_f32_e64 s[0:1], 0, v7
	v_add_u32_e32 v7, 1, v5
	s_nop 0
	v_cndmask_b32_e64 v6, v5, v6, s[0:1]
	v_fma_f32 v5, -v7, v5, v4
	v_cmp_lt_f32_e64 s[0:1], 0, v5
	s_nop 1
	v_cndmask_b32_e64 v5, v6, v7, s[0:1]
	v_mul_f32_e32 v6, 0x37800000, v5
	v_cndmask_b32_e32 v5, v5, v6, vcc
	v_cmp_class_f32_e32 vcc, v4, v200
	s_nop 1
	v_cndmask_b32_e32 v4, v5, v4, vcc
	v_div_scale_f32 v5, s[0:1], v4, v4, 1.0
	v_rcp_f32_e32 v6, v5
	s_mov_b32 s0, 0x19b03000
	v_fma_f32 v7, -v5, v6, 1.0
	v_fmac_f32_e32 v6, v7, v6
	v_div_scale_f32 v7, vcc, 1.0, v4, 1.0
	v_mul_f32_e32 v26, v7, v6
	v_fma_f32 v28, -v5, v26, v7
	v_fmac_f32_e32 v26, v28, v6
	v_fma_f32 v5, -v5, v26, v7
	v_div_fmas_f32 v5, v5, v6, v26
	v_div_fixup_f32 v26, v5, v4, 1.0
	flat_load_dwordx4 v[4:7], v[22:23]
	flat_load_dwordx4 v[42:45], v[22:23] offset:16
	flat_load_dwordx4 v[46:49], v[24:25]
	flat_load_dwordx4 v[50:53], v[24:25] offset:16
	v_lshl_add_u64 v[28:29], s[14:15], 0, v[20:21]
	v_add_co_u32_e32 v28, vcc, s0, v28
	v_pk_mul_f32 v[32:33], v[32:33], v[26:27] op_sel_hi:[1,0]
	s_nop 0
	v_addc_co_u32_e32 v29, vcc, 0, v29, vcc
	global_load_dwordx4 v[54:57], v[28:29], off offset:2048
	global_load_dwordx4 v[214:217], v[22:23], off offset:2048
	global_load_dwordx4 v[218:221], v[22:23], off offset:2064
	global_load_dwordx4 v[222:225], v[24:25], off offset:2048
	global_load_dwordx4 v[226:229], v[24:25], off offset:2064
	global_load_dwordx4 v[230:233], v[28:29], off offset:3072
	v_pk_mul_f32 v[16:17], v[16:17], v[26:27] op_sel_hi:[1,0]
	v_pk_mul_f32 v[12:13], v[12:13], v[26:27] op_sel_hi:[1,0]
	s_mov_b32 s0, 0x2ce00000
	v_pk_mul_f32 v[14:15], v[14:15], v[26:27] op_sel_hi:[1,0]
	v_pk_mul_f32 v[8:9], v[8:9], v[26:27] op_sel_hi:[1,0]
	v_pk_mul_f32 v[2:3], v[2:3], v[26:27] op_sel_hi:[1,0]
	s_waitcnt vmcnt(0) lgkmcnt(0)
	v_pk_fma_f32 v[4:5], v[4:5], v[32:33], v[46:47]
	v_pk_fma_f32 v[6:7], v[6:7], v[16:17], v[48:49]
	v_mul_f32_e32 v16, 0xbfb8aa3b, v4
	v_mul_f32_e32 v17, 0xbfb8aa3b, v5
	v_exp_f32_e32 v16, v16
	v_exp_f32_e32 v17, v17
	v_mul_f32_e32 v32, 0xbfb8aa3b, v6
	v_mul_f32_e32 v33, 0xbfb8aa3b, v7
	v_exp_f32_e32 v32, v32
	v_exp_f32_e32 v33, v33
	v_add_f32_e32 v16, 1.0, v16
	v_add_f32_e32 v17, 1.0, v17
	v_rcp_f32_e32 v16, v16
	v_rcp_f32_e32 v17, v17
	v_add_f32_e32 v32, 1.0, v32
	v_add_f32_e32 v33, 1.0, v33
	v_rcp_f32_e32 v32, v32
	v_rcp_f32_e32 v33, v33
	v_pk_mul_f32 v[4:5], v[4:5], v[16:17]
	v_pk_mul_f32 v[16:17], v[30:31], v[26:27] op_sel_hi:[1,0]
	v_pk_fma_f32 v[12:13], v[44:45], v[12:13], v[52:53]
	v_pk_mul_f32 v[6:7], v[6:7], v[32:33]
	v_pk_fma_f32 v[16:17], v[42:43], v[16:17], v[50:51]
	v_mul_f32_e32 v32, 0xbfb8aa3b, v12
	v_mul_f32_e32 v33, 0xbfb8aa3b, v13
	v_mul_f32_e32 v30, 0xbfb8aa3b, v16
	v_mul_f32_e32 v31, 0xbfb8aa3b, v17
	v_exp_f32_e32 v32, v32
	v_exp_f32_e32 v33, v33
	v_exp_f32_e32 v30, v30
	v_exp_f32_e32 v31, v31
	v_add_f32_e32 v32, 1.0, v32
	v_add_f32_e32 v33, 1.0, v33
	v_add_f32_e32 v30, 1.0, v30
	v_add_f32_e32 v31, 1.0, v31
	v_rcp_f32_e32 v32, v32
	v_rcp_f32_e32 v33, v33
	v_rcp_f32_e32 v30, v30
	v_rcp_f32_e32 v31, v31
	v_lshlrev_b32_e32 v58, 16, v54
	v_and_b32_e32 v59, 0xffff0000, v54
	v_lshlrev_b32_e32 v54, 16, v55
	v_and_b32_e32 v55, 0xffff0000, v55
	v_lshlrev_b32_e32 v60, 16, v56
	v_and_b32_e32 v61, 0xffff0000, v56
	v_lshlrev_b32_e32 v56, 16, v57
	v_and_b32_e32 v57, 0xffff0000, v57
	v_pk_mul_f32 v[12:13], v[12:13], v[32:33]
	v_pk_mul_f32 v[6:7], v[6:7], v[54:55]
	v_pk_mul_f32 v[4:5], v[4:5], v[58:59]
	v_pk_mul_f32 v[16:17], v[16:17], v[30:31]
	v_pk_mul_f32 v[12:13], v[12:13], v[56:57]
	v_pk_mul_f32 v[16:17], v[16:17], v[60:61]
	v_cvt_pk_bf16_f32 v4, v4, v5
	v_cvt_pk_bf16_f32 v5, v6, v7
	s_nop 0
	v_cvt_pk_bf16_f32 v6, v16, v17
	v_cvt_pk_bf16_f32 v7, v12, v13
	v_lshl_add_u64 v[12:13], s[10:11], 0, v[20:21]
	v_add_co_u32_e32 v12, vcc, s0, v12
	s_add_u32 s10, s10, 0x4000
	s_nop 0
	v_addc_co_u32_e32 v13, vcc, 0, v13, vcc
	global_store_dwordx4 v[12:13], v[4:7], off
	s_nop 0
	s_nop 0
	s_nop 0
	s_nop 0
	s_nop 0
	s_nop 0
	s_addc_u32 s11, s11, 0
	s_add_u32 s14, s14, 0x38000
	v_add_co_u32_e32 v39, vcc, 8, v39
	s_addc_u32 s15, s15, 0
	s_and_b64 vcc, exec, vcc
	s_nop 0
	v_pk_fma_f32 v[4:5], v[214:215], v[14:15], v[222:223]
	v_pk_fma_f32 v[6:7], v[216:217], v[8:9], v[224:225]
	v_mul_f32_e32 v8, 0xbfb8aa3b, v4
	v_mul_f32_e32 v9, 0xbfb8aa3b, v5
	v_exp_f32_e32 v8, v8
	v_exp_f32_e32 v9, v9
	v_mul_f32_e32 v14, 0xbfb8aa3b, v6
	v_mul_f32_e32 v15, 0xbfb8aa3b, v7
	v_exp_f32_e32 v14, v14
	v_exp_f32_e32 v15, v15
	v_add_f32_e32 v8, 1.0, v8
	v_add_f32_e32 v9, 1.0, v9
	v_rcp_f32_e32 v8, v8
	v_rcp_f32_e32 v9, v9
	v_add_f32_e32 v14, 1.0, v14
	v_add_f32_e32 v15, 1.0, v15
	v_rcp_f32_e32 v14, v14
	v_rcp_f32_e32 v15, v15
	v_pk_mul_f32 v[4:5], v[4:5], v[8:9]
	v_pk_mul_f32 v[8:9], v[10:11], v[26:27] op_sel_hi:[1,0]
	v_pk_fma_f32 v[2:3], v[218:219], v[2:3], v[226:227]
	v_pk_fma_f32 v[8:9], v[220:221], v[8:9], v[228:229]
	v_pk_mul_f32 v[6:7], v[6:7], v[14:15]
	v_mul_f32_e32 v10, 0xbfb8aa3b, v2
	v_mul_f32_e32 v11, 0xbfb8aa3b, v3
	v_mul_f32_e32 v14, 0xbfb8aa3b, v8
	v_mul_f32_e32 v15, 0xbfb8aa3b, v9
	v_exp_f32_e32 v10, v10
	v_exp_f32_e32 v11, v11
	v_exp_f32_e32 v14, v14
	v_exp_f32_e32 v15, v15
	v_add_f32_e32 v10, 1.0, v10
	v_add_f32_e32 v11, 1.0, v11
	v_add_f32_e32 v14, 1.0, v14
	v_add_f32_e32 v15, 1.0, v15
	v_rcp_f32_e32 v10, v10
	v_rcp_f32_e32 v11, v11
	v_rcp_f32_e32 v14, v14
	v_rcp_f32_e32 v15, v15
	v_lshlrev_b32_e32 v16, 16, v230
	v_and_b32_e32 v17, 0xffff0000, v230
	v_lshlrev_b32_e32 v28, 16, v231
	v_and_b32_e32 v29, 0xffff0000, v231
	v_lshlrev_b32_e32 v50, 16, v232
	v_and_b32_e32 v51, 0xffff0000, v232
	v_lshlrev_b32_e32 v52, 16, v233
	v_and_b32_e32 v53, 0xffff0000, v233
	v_pk_mul_f32 v[4:5], v[4:5], v[16:17]
	v_pk_mul_f32 v[2:3], v[2:3], v[10:11]
	v_pk_mul_f32 v[8:9], v[8:9], v[14:15]
	v_pk_mul_f32 v[6:7], v[6:7], v[28:29]
	v_pk_mul_f32 v[8:9], v[8:9], v[52:53]
	v_pk_mul_f32 v[10:11], v[2:3], v[50:51]
	v_cvt_pk_bf16_f32 v2, v4, v5
	v_cvt_pk_bf16_f32 v3, v6, v7
	s_nop 0
	v_cvt_pk_bf16_f32 v4, v10, v11
	v_cvt_pk_bf16_f32 v5, v8, v9
	global_store_dwordx4 v[12:13], v[2:5], off offset:1024
	s_cbranch_vccnz .LBB0_635
	s_branch .LBB0_628
